# P2 heavy epilogue: the 16 row sum-of-squares cross-lane reductions use v_permlane16/32_swap register exchanges instead of two LDS round trips each (same adds, same order)
# baseline (speedup 1.0000x reference)
.LBB0_208:
	s_andn2_b64 vcc, exec, s[62:63]
	s_cbranch_vccnz .LBB0_261
	v_mul_f32_e32 v105, v133, v133
	v_mul_f32_e32 v106, v135, v135
	v_fmac_f32_e32 v105, v132, v132
	v_fmac_f32_e32 v106, v134, v134
	v_add_f32_e32 v105, v105, v106
	v_mul_f32_e32 v106, v129, v129
	v_fmac_f32_e32 v106, v128, v128
	v_add_f32_e32 v105, v105, v106
	v_mul_f32_e32 v106, v131, v131
	v_fmac_f32_e32 v106, v130, v130
	v_add_f32_e32 v105, v106, v105
	v_mov_b32_e32 v107, v105
	s_nop 1
	v_permlane16_swap_b32_e32 v107, v105
	v_lshlrev_b32_e32 v106, 2, v152
	v_lshl_add_u32 v106, v219, 6, v106
	v_xor_b32_e32 v106, 0x80, v106
	v_lshlrev_b32_e32 v144, 5, v162
	s_waitcnt lgkmcnt(0)
	v_add_f32_e32 v107, v105, v107
	v_mov_b32_e32 v108, v107
	s_nop 1
	v_permlane32_swap_b32_e32 v108, v107
	v_cmp_eq_u32_e32 vcc, 0, v219
	v_add_u32_e32 v105, s85, v144
	s_and_saveexec_b64 s[62:63], vcc
	s_cbranch_execz .LBB0_211
	s_waitcnt lgkmcnt(0)
	v_add_f32_e32 v107, v107, v108
	ds_write_b32 v105, v107
.LBB0_211:
	s_or_b64 exec, exec, s[62:63]
	v_mul_f32_e32 v107, v125, v125
	s_waitcnt lgkmcnt(0)
	v_mul_f32_e32 v108, v127, v127
	v_fmac_f32_e32 v107, v124, v124
	v_fmac_f32_e32 v108, v126, v126
	v_add_f32_e32 v107, v107, v108
	v_mul_f32_e32 v108, v121, v121
	v_fmac_f32_e32 v108, v120, v120
	v_add_f32_e32 v107, v107, v108
	v_mul_f32_e32 v108, v123, v123
	v_fmac_f32_e32 v108, v122, v122
	v_add_f32_e32 v107, v108, v107
	v_mov_b32_e32 v108, v107
	s_nop 1
	v_permlane16_swap_b32_e32 v108, v107
	s_waitcnt lgkmcnt(0)
	v_add_f32_e32 v107, v107, v108
	v_mov_b32_e32 v108, v107
	s_nop 1
	v_permlane32_swap_b32_e32 v108, v107
	s_and_saveexec_b64 s[62:63], vcc
	s_cbranch_execz .LBB0_213
	s_waitcnt lgkmcnt(0)
	v_add_f32_e32 v107, v107, v108
	ds_write_b32 v105, v107 offset:16
.LBB0_213:
	s_or_b64 exec, exec, s[62:63]
	v_mul_f32_e32 v107, v117, v117
	s_waitcnt lgkmcnt(0)
	v_mul_f32_e32 v108, v119, v119
	v_fmac_f32_e32 v107, v116, v116
	v_fmac_f32_e32 v108, v118, v118
	v_add_f32_e32 v107, v107, v108
	v_mul_f32_e32 v108, v113, v113
	v_fmac_f32_e32 v108, v112, v112
	v_add_f32_e32 v107, v107, v108
	v_mul_f32_e32 v108, v115, v115
	v_fmac_f32_e32 v108, v114, v114
	v_add_f32_e32 v107, v108, v107
	v_mov_b32_e32 v108, v107
	s_nop 1
	v_permlane16_swap_b32_e32 v108, v107
	s_waitcnt lgkmcnt(0)
	v_add_f32_e32 v107, v107, v108
	v_mov_b32_e32 v108, v107
	s_nop 1
	v_permlane32_swap_b32_e32 v108, v107
	s_and_saveexec_b64 s[62:63], vcc
	s_cbranch_execz .LBB0_215
	s_waitcnt lgkmcnt(0)
	v_add_f32_e32 v107, v107, v108
	ds_write_b32 v105, v107 offset:512
.LBB0_215:
	s_or_b64 exec, exec, s[62:63]
	v_mul_f32_e32 v107, v101, v101
	s_waitcnt lgkmcnt(0)
	v_mul_f32_e32 v108, v103, v103
	v_fmac_f32_e32 v107, v100, v100
	v_fmac_f32_e32 v108, v102, v102
	v_add_f32_e32 v107, v107, v108
	v_mul_f32_e32 v108, v97, v97
	v_fmac_f32_e32 v108, v96, v96
	v_add_f32_e32 v107, v107, v108
	v_mul_f32_e32 v108, v99, v99
	v_fmac_f32_e32 v108, v98, v98
	v_add_f32_e32 v107, v108, v107
	v_mov_b32_e32 v108, v107
	s_nop 1
	v_permlane16_swap_b32_e32 v108, v107
	s_waitcnt lgkmcnt(0)
	v_add_f32_e32 v107, v107, v108
	v_mov_b32_e32 v108, v107
	s_nop 1
	v_permlane32_swap_b32_e32 v108, v107
	s_and_saveexec_b64 s[62:63], vcc
	s_cbranch_execz .LBB0_217
	s_waitcnt lgkmcnt(0)
	v_add_f32_e32 v107, v107, v108
	ds_write_b32 v105, v107 offset:528
.LBB0_217:
	s_or_b64 exec, exec, s[62:63]
	v_mul_f32_e32 v107, v93, v93
	s_waitcnt lgkmcnt(0)
	v_mul_f32_e32 v108, v95, v95
	v_fmac_f32_e32 v107, v92, v92
	v_fmac_f32_e32 v108, v94, v94
	v_add_f32_e32 v107, v107, v108
	v_mul_f32_e32 v108, v89, v89
	v_fmac_f32_e32 v108, v88, v88
	v_add_f32_e32 v107, v107, v108
	v_mul_f32_e32 v108, v91, v91
	v_fmac_f32_e32 v108, v90, v90
	v_add_f32_e32 v107, v108, v107
	v_mov_b32_e32 v108, v107
	s_nop 1
	v_permlane16_swap_b32_e32 v108, v107
	s_waitcnt lgkmcnt(0)
	v_add_f32_e32 v107, v107, v108
	v_mov_b32_e32 v108, v107
	s_nop 1
	v_permlane32_swap_b32_e32 v108, v107
	s_and_saveexec_b64 s[62:63], vcc
	s_cbranch_execz .LBB0_219
	s_waitcnt lgkmcnt(0)
	v_add_f32_e32 v107, v107, v108
	ds_write_b32 v105, v107 offset:1024
.LBB0_219:
	s_or_b64 exec, exec, s[62:63]
	v_mul_f32_e32 v107, v85, v85
	s_waitcnt lgkmcnt(0)
	v_mul_f32_e32 v108, v87, v87
	v_fmac_f32_e32 v107, v84, v84
	v_fmac_f32_e32 v108, v86, v86
	v_add_f32_e32 v107, v107, v108
	v_mul_f32_e32 v108, v81, v81
	v_fmac_f32_e32 v108, v80, v80
	v_add_f32_e32 v107, v107, v108
	v_mul_f32_e32 v108, v83, v83
	v_fmac_f32_e32 v108, v82, v82
	v_add_f32_e32 v107, v108, v107
	v_mov_b32_e32 v108, v107
	s_nop 1
	v_permlane16_swap_b32_e32 v108, v107
	s_waitcnt lgkmcnt(0)
	v_add_f32_e32 v107, v107, v108
	v_mov_b32_e32 v108, v107
	s_nop 1
	v_permlane32_swap_b32_e32 v108, v107
	s_and_saveexec_b64 s[62:63], vcc
	s_cbranch_execz .LBB0_221
	s_waitcnt lgkmcnt(0)
	v_add_f32_e32 v107, v107, v108
	ds_write_b32 v105, v107 offset:1040
.LBB0_221:
	s_or_b64 exec, exec, s[62:63]
	v_mul_f32_e32 v107, v77, v77
	s_waitcnt lgkmcnt(0)
	v_mul_f32_e32 v108, v79, v79
	v_fmac_f32_e32 v107, v76, v76
	v_fmac_f32_e32 v108, v78, v78
	v_add_f32_e32 v107, v107, v108
	v_mul_f32_e32 v108, v73, v73
	v_fmac_f32_e32 v108, v72, v72
	v_add_f32_e32 v107, v107, v108
	v_mul_f32_e32 v108, v75, v75
	v_fmac_f32_e32 v108, v74, v74
	v_add_f32_e32 v107, v108, v107
	v_mov_b32_e32 v108, v107
	s_nop 1
	v_permlane16_swap_b32_e32 v108, v107
	s_waitcnt lgkmcnt(0)
	v_add_f32_e32 v107, v107, v108
	v_mov_b32_e32 v108, v107
	s_nop 1
	v_permlane32_swap_b32_e32 v108, v107
	s_and_saveexec_b64 s[62:63], vcc
	s_cbranch_execz .LBB0_223
	s_waitcnt lgkmcnt(0)
	v_add_f32_e32 v107, v107, v108
	ds_write_b32 v105, v107 offset:1536
.LBB0_223:
	s_or_b64 exec, exec, s[62:63]
	v_mul_f32_e32 v107, v69, v69
	s_waitcnt lgkmcnt(0)
	v_mul_f32_e32 v108, v71, v71
	v_fmac_f32_e32 v107, v68, v68
	v_fmac_f32_e32 v108, v70, v70
	v_add_f32_e32 v107, v107, v108
	v_mul_f32_e32 v108, v65, v65
	v_fmac_f32_e32 v108, v64, v64
	v_add_f32_e32 v107, v107, v108
	v_mul_f32_e32 v108, v67, v67
	v_fmac_f32_e32 v108, v66, v66
	v_add_f32_e32 v107, v108, v107
	v_mov_b32_e32 v108, v107
	s_nop 1
	v_permlane16_swap_b32_e32 v108, v107
	s_waitcnt lgkmcnt(0)
	v_add_f32_e32 v107, v107, v108
	v_mov_b32_e32 v108, v107
	s_nop 1
	v_permlane32_swap_b32_e32 v108, v107
	s_and_saveexec_b64 s[62:63], vcc
	s_cbranch_execz .LBB0_225
	s_waitcnt lgkmcnt(0)
	v_add_f32_e32 v107, v107, v108
	ds_write_b32 v105, v107 offset:1552
.LBB0_225:
	s_or_b64 exec, exec, s[62:63]
	v_mul_f32_e32 v107, v61, v61
	s_waitcnt lgkmcnt(0)
	v_mul_f32_e32 v108, v63, v63
	v_fmac_f32_e32 v107, v60, v60
	v_fmac_f32_e32 v108, v62, v62
	v_add_f32_e32 v107, v107, v108
	v_mul_f32_e32 v108, v57, v57
	v_fmac_f32_e32 v108, v56, v56
	v_add_f32_e32 v107, v107, v108
	v_mul_f32_e32 v108, v59, v59
	v_fmac_f32_e32 v108, v58, v58
	v_add_f32_e32 v107, v108, v107
	v_mov_b32_e32 v108, v107
	s_nop 1
	v_permlane16_swap_b32_e32 v108, v107
	s_waitcnt lgkmcnt(0)
	v_add_f32_e32 v107, v107, v108
	v_mov_b32_e32 v108, v107
	s_nop 1
	v_permlane32_swap_b32_e32 v108, v107
	s_and_saveexec_b64 s[62:63], vcc
	s_cbranch_execz .LBB0_227
	s_waitcnt lgkmcnt(0)
	v_add_f32_e32 v107, v107, v108
	ds_write_b32 v105, v107 offset:4096
.LBB0_227:
	s_or_b64 exec, exec, s[62:63]
	v_mul_f32_e32 v107, v53, v53
	s_waitcnt lgkmcnt(0)
	v_mul_f32_e32 v108, v55, v55
	v_fmac_f32_e32 v107, v52, v52
	v_fmac_f32_e32 v108, v54, v54
	v_add_f32_e32 v107, v107, v108
	v_mul_f32_e32 v108, v49, v49
	v_fmac_f32_e32 v108, v48, v48
	v_add_f32_e32 v107, v107, v108
	v_mul_f32_e32 v108, v51, v51
	v_fmac_f32_e32 v108, v50, v50
	v_add_f32_e32 v107, v108, v107
	v_mov_b32_e32 v108, v107
	s_nop 1
	v_permlane16_swap_b32_e32 v108, v107
	s_waitcnt lgkmcnt(0)
	v_add_f32_e32 v107, v107, v108
	v_mov_b32_e32 v108, v107
	s_nop 1
	v_permlane32_swap_b32_e32 v108, v107
	s_and_saveexec_b64 s[62:63], vcc
	s_cbranch_execz .LBB0_229
	s_waitcnt lgkmcnt(0)
	v_add_f32_e32 v107, v107, v108
	ds_write_b32 v105, v107 offset:4112
.LBB0_229:
	s_or_b64 exec, exec, s[62:63]
	v_mul_f32_e32 v107, v45, v45
	s_waitcnt lgkmcnt(0)
	v_mul_f32_e32 v108, v47, v47
	v_fmac_f32_e32 v107, v44, v44
	v_fmac_f32_e32 v108, v46, v46
	v_add_f32_e32 v107, v107, v108
	v_mul_f32_e32 v108, v41, v41
	v_fmac_f32_e32 v108, v40, v40
	v_add_f32_e32 v107, v107, v108
	v_mul_f32_e32 v108, v43, v43
	v_fmac_f32_e32 v108, v42, v42
	v_add_f32_e32 v107, v108, v107
	v_mov_b32_e32 v108, v107
	s_nop 1
	v_permlane16_swap_b32_e32 v108, v107
	s_waitcnt lgkmcnt(0)
	v_add_f32_e32 v107, v107, v108
	v_mov_b32_e32 v108, v107
	s_nop 1
	v_permlane32_swap_b32_e32 v108, v107
	s_and_saveexec_b64 s[62:63], vcc
	s_cbranch_execz .LBB0_231
	s_waitcnt lgkmcnt(0)
	v_add_f32_e32 v107, v107, v108
	ds_write_b32 v105, v107 offset:4608
.LBB0_231:
	s_or_b64 exec, exec, s[62:63]
	v_mul_f32_e32 v107, v37, v37
	s_waitcnt lgkmcnt(0)
	v_mul_f32_e32 v108, v39, v39
	v_fmac_f32_e32 v107, v36, v36
	v_fmac_f32_e32 v108, v38, v38
	v_add_f32_e32 v107, v107, v108
	v_mul_f32_e32 v108, v33, v33
	v_fmac_f32_e32 v108, v32, v32
	v_add_f32_e32 v107, v107, v108
	v_mul_f32_e32 v108, v35, v35
	v_fmac_f32_e32 v108, v34, v34
	v_add_f32_e32 v107, v108, v107
	v_mov_b32_e32 v108, v107
	s_nop 1
	v_permlane16_swap_b32_e32 v108, v107
	s_waitcnt lgkmcnt(0)
	v_add_f32_e32 v107, v107, v108
	v_mov_b32_e32 v108, v107
	s_nop 1
	v_permlane32_swap_b32_e32 v108, v107
	s_and_saveexec_b64 s[62:63], vcc
	s_cbranch_execz .LBB0_233
	s_waitcnt lgkmcnt(0)
	v_add_f32_e32 v107, v107, v108
	ds_write_b32 v105, v107 offset:4624
.LBB0_233:
	s_or_b64 exec, exec, s[62:63]
	v_mul_f32_e32 v107, v29, v29
	s_waitcnt lgkmcnt(0)
	v_mul_f32_e32 v108, v31, v31
	v_fmac_f32_e32 v107, v28, v28
	v_fmac_f32_e32 v108, v30, v30
	v_add_f32_e32 v107, v107, v108
	v_mul_f32_e32 v108, v25, v25
	v_fmac_f32_e32 v108, v24, v24
	v_add_f32_e32 v107, v107, v108
	v_mul_f32_e32 v108, v27, v27
	v_fmac_f32_e32 v108, v26, v26
	v_add_f32_e32 v107, v108, v107
	v_mov_b32_e32 v108, v107
	s_nop 1
	v_permlane16_swap_b32_e32 v108, v107
	s_waitcnt lgkmcnt(0)
	v_add_f32_e32 v107, v107, v108
	v_mov_b32_e32 v108, v107
	s_nop 1
	v_permlane32_swap_b32_e32 v108, v107
	s_and_saveexec_b64 s[62:63], vcc
	s_cbranch_execz .LBB0_235
	s_waitcnt lgkmcnt(0)
	v_add_f32_e32 v107, v107, v108
	ds_write_b32 v105, v107 offset:5120
.LBB0_235:
	s_or_b64 exec, exec, s[62:63]
	v_mul_f32_e32 v107, v21, v21
	s_waitcnt lgkmcnt(0)
	v_mul_f32_e32 v108, v23, v23
	v_fmac_f32_e32 v107, v20, v20
	v_fmac_f32_e32 v108, v22, v22
	v_add_f32_e32 v107, v107, v108
	v_mul_f32_e32 v108, v17, v17
	v_fmac_f32_e32 v108, v16, v16
	v_add_f32_e32 v107, v107, v108
	v_mul_f32_e32 v108, v19, v19
	v_fmac_f32_e32 v108, v18, v18
	v_add_f32_e32 v107, v108, v107
	v_mov_b32_e32 v108, v107
	s_nop 1
	v_permlane16_swap_b32_e32 v108, v107
	s_waitcnt lgkmcnt(0)
	v_add_f32_e32 v107, v107, v108
	v_mov_b32_e32 v108, v107
	s_nop 1
	v_permlane32_swap_b32_e32 v108, v107
	s_and_saveexec_b64 s[62:63], vcc
	s_cbranch_execz .LBB0_237
	s_waitcnt lgkmcnt(0)
	v_add_f32_e32 v107, v107, v108
	ds_write_b32 v105, v107 offset:5136
.LBB0_237:
	s_or_b64 exec, exec, s[62:63]
	v_mul_f32_e32 v107, v13, v13
	s_waitcnt lgkmcnt(0)
	v_mul_f32_e32 v108, v15, v15
	v_fmac_f32_e32 v107, v12, v12
	v_fmac_f32_e32 v108, v14, v14
	v_add_f32_e32 v107, v107, v108
	v_mul_f32_e32 v108, v9, v9
	v_fmac_f32_e32 v108, v8, v8
	v_add_f32_e32 v107, v107, v108
	v_mul_f32_e32 v108, v11, v11
	v_fmac_f32_e32 v108, v10, v10
	v_add_f32_e32 v107, v108, v107
	v_mov_b32_e32 v108, v107
	s_nop 1
	v_permlane16_swap_b32_e32 v108, v107
	s_waitcnt lgkmcnt(0)
	v_add_f32_e32 v107, v107, v108
	v_mov_b32_e32 v108, v107
	s_nop 1
	v_permlane32_swap_b32_e32 v108, v107
	s_and_saveexec_b64 s[62:63], vcc
	s_cbranch_execz .LBB0_239
	s_waitcnt lgkmcnt(0)
	v_add_f32_e32 v107, v107, v108
	ds_write_b32 v105, v107 offset:5632
.LBB0_239:
	s_or_b64 exec, exec, s[62:63]
	v_mul_f32_e32 v107, v5, v5
	s_waitcnt lgkmcnt(0)
	v_mul_f32_e32 v108, v7, v7
	v_fmac_f32_e32 v107, v4, v4
	v_fmac_f32_e32 v108, v6, v6
	v_add_f32_e32 v107, v107, v108
	v_mul_f32_e32 v108, v1, v1
	v_fmac_f32_e32 v108, v0, v0
	v_add_f32_e32 v107, v107, v108
	v_mul_f32_e32 v108, v3, v3
	v_fmac_f32_e32 v108, v2, v2
	v_add_f32_e32 v107, v108, v107
	v_mov_b32_e32 v108, v107
	s_nop 1
	v_permlane16_swap_b32_e32 v108, v107
	s_waitcnt lgkmcnt(0)
	v_add_f32_e32 v107, v107, v108
	v_mov_b32_e32 v106, v107
	s_nop 1
	v_permlane32_swap_b32_e32 v106, v107
	s_and_saveexec_b64 s[62:63], vcc
	s_cbranch_execz .LBB0_241
	s_waitcnt lgkmcnt(0)
	v_add_f32_e32 v106, v107, v106
	ds_write_b32 v105, v106 offset:5648
